# stick-breaking unit epilogue: quad transposes (DPP + v_perm) so each lane stores 8 B (16 dwordx2 stores instead of 64 2-byte stores); on top of final combined
# baseline (speedup 1.0000x reference)
; __device__ __forceinline__ bf16_t f2bf(float f) { unsigned u = __float_as_uint(f); u += 0x7FFFu + ((u >> 16) & 1u); return (bf16_t)(u >> 16); }
; __device__ __forceinline__ void sb_unit(LAS unsigned char* lds, const bf16_t* qkv, bf16_t* attout, int b, int h, int qb, int wid, int) {
;     ...
;     asm volatile("" : "+v"(hi), "+v"(r32));
;     bf16_t* op = attout + (size_t)(b * SEQ + q0 + 4 * hi) * DM + h * 128 + r32;
; #pragma unroll
;     for (int r = 0; r < 16; ++r) {
; #pragma unroll
;         for (int d0 = 0; d0 < 4; ++d0) op[d0 * 32] = f2bf(o[d0][r]);
;         op += ((r & 3) == 3 ? 5 : 1) * DM; asm volatile("" : "+v"(op) :: "memory"); }
.LBB0_304:
	s_lshl_b32 s1, s33, 12
	s_add_i32 s43, s43, s1
	s_lshl_b32 s0, s42, 7
	v_lshl_add_u32 v2, v193, 2, s43
	v_and_b32_e32 v3, 3, v192
	v_add_u32_e32 v2, v2, v3
	v_ashrrev_i32_e32 v3, 31, v2
	v_lshlrev_b64 v[2:3], 12, v[2:3]
	v_lshl_add_u64 v[2:3], s[44:45], 0, v[2:3]
	s_lshl_b32 s46, s0, 1
	v_lshl_add_u64 v[2:3], v[2:3], 0, s[46:47]
	v_and_b32_e32 v0, 28, v192
	v_lshlrev_b32_e32 v0, 1, v0
	v_add_co_u32_e32 v2, vcc, v2, v0
	s_nop 1
	v_addc_co_u32_e32 v3, vcc, 0, v3, vcc
	v_and_b32_e32 v0, 1, v192
	v_sub_u32_e32 v0, 0, v0
	v_and_b32_e32 v0, 0x6060606, v0
	s_mov_b32 s98, 0xcccccccc
	s_mov_b32 s99, 0xcccccccc
	s_mov_b64 s[100:101], 0x8000
	v_xor_b32_e32 v0, 0x1000504, v0
	v_cvt_pk_bf16_f32 v112, v112, v113
	v_cvt_pk_bf16_f32 v80, v80, v81
	v_cvt_pk_bf16_f32 v96, v96, v97
	v_cvt_pk_bf16_f32 v128, v128, v129
	v_cvt_pk_bf16_f32 v114, v114, v115
	v_cvt_pk_bf16_f32 v82, v82, v83
	v_cvt_pk_bf16_f32 v98, v98, v99
	v_cvt_pk_bf16_f32 v130, v130, v131
	v_mov_b32_dpp v113, v112 quad_perm:[1,0,3,2] row_mask:0xf bank_mask:0xf
	v_mov_b32_dpp v81, v80 quad_perm:[1,0,3,2] row_mask:0xf bank_mask:0xf
	v_mov_b32_dpp v97, v96 quad_perm:[1,0,3,2] row_mask:0xf bank_mask:0xf
	v_mov_b32_dpp v129, v128 quad_perm:[1,0,3,2] row_mask:0xf bank_mask:0xf
	v_mov_b32_dpp v115, v114 quad_perm:[1,0,3,2] row_mask:0xf bank_mask:0xf
	v_mov_b32_dpp v83, v82 quad_perm:[1,0,3,2] row_mask:0xf bank_mask:0xf
	v_mov_b32_dpp v99, v98 quad_perm:[1,0,3,2] row_mask:0xf bank_mask:0xf
	v_mov_b32_dpp v131, v130 quad_perm:[1,0,3,2] row_mask:0xf bank_mask:0xf
	v_perm_b32 v112, v112, v113, v0
	v_perm_b32 v80, v80, v81, v0
	v_perm_b32 v96, v96, v97, v0
	v_perm_b32 v128, v128, v129, v0
	v_perm_b32 v114, v114, v115, v0
	v_perm_b32 v82, v82, v83, v0
	v_perm_b32 v98, v98, v99, v0
	v_perm_b32 v130, v130, v131, v0
	v_cndmask_b32_e64 v113, v114, v112, s[98:99]
	v_cndmask_b32_e64 v81, v82, v80, s[98:99]
	v_cndmask_b32_e64 v97, v98, v96, s[98:99]
	v_cndmask_b32_e64 v129, v130, v128, s[98:99]
	v_mov_b32_dpp v115, v113 quad_perm:[2,3,0,1] row_mask:0xf bank_mask:0xf
	v_mov_b32_dpp v83, v81 quad_perm:[2,3,0,1] row_mask:0xf bank_mask:0xf
	v_mov_b32_dpp v99, v97 quad_perm:[2,3,0,1] row_mask:0xf bank_mask:0xf
	v_mov_b32_dpp v131, v129 quad_perm:[2,3,0,1] row_mask:0xf bank_mask:0xf
	v_cndmask_b32_e64 v113, v115, v114, s[98:99]
	v_cndmask_b32_e64 v81, v83, v82, s[98:99]
	v_cndmask_b32_e64 v97, v99, v98, s[98:99]
	v_cndmask_b32_e64 v129, v131, v130, s[98:99]
	v_cndmask_b32_e64 v112, v112, v115, s[98:99]
	v_cndmask_b32_e64 v80, v80, v83, s[98:99]
	v_cndmask_b32_e64 v96, v96, v99, s[98:99]
	v_cndmask_b32_e64 v128, v128, v131, s[98:99]
	global_store_dwordx2 v[2:3], v[112:113], off
	global_store_dwordx2 v[2:3], v[80:81], off offset:64
	global_store_dwordx2 v[2:3], v[96:97], off offset:128
	global_store_dwordx2 v[2:3], v[128:129], off offset:192
	v_lshl_add_u64 v[2:3], v[2:3], 0, s[100:101]
	v_cvt_pk_bf16_f32 v116, v116, v117
	v_cvt_pk_bf16_f32 v84, v84, v85
	v_cvt_pk_bf16_f32 v100, v100, v101
	v_cvt_pk_bf16_f32 v132, v132, v133
	v_cvt_pk_bf16_f32 v118, v118, v119
	v_cvt_pk_bf16_f32 v86, v86, v87
	v_cvt_pk_bf16_f32 v102, v102, v103
	v_cvt_pk_bf16_f32 v134, v134, v135
	v_mov_b32_dpp v117, v116 quad_perm:[1,0,3,2] row_mask:0xf bank_mask:0xf
	v_mov_b32_dpp v85, v84 quad_perm:[1,0,3,2] row_mask:0xf bank_mask:0xf
	v_mov_b32_dpp v101, v100 quad_perm:[1,0,3,2] row_mask:0xf bank_mask:0xf
	v_mov_b32_dpp v133, v132 quad_perm:[1,0,3,2] row_mask:0xf bank_mask:0xf
	v_mov_b32_dpp v119, v118 quad_perm:[1,0,3,2] row_mask:0xf bank_mask:0xf
	v_mov_b32_dpp v87, v86 quad_perm:[1,0,3,2] row_mask:0xf bank_mask:0xf
	v_mov_b32_dpp v103, v102 quad_perm:[1,0,3,2] row_mask:0xf bank_mask:0xf
	v_mov_b32_dpp v135, v134 quad_perm:[1,0,3,2] row_mask:0xf bank_mask:0xf
	v_perm_b32 v116, v116, v117, v0
	v_perm_b32 v84, v84, v85, v0
	v_perm_b32 v100, v100, v101, v0
	v_perm_b32 v132, v132, v133, v0
	v_perm_b32 v118, v118, v119, v0
	v_perm_b32 v86, v86, v87, v0
	v_perm_b32 v102, v102, v103, v0
	v_perm_b32 v134, v134, v135, v0
	v_cndmask_b32_e64 v117, v118, v116, s[98:99]
	v_cndmask_b32_e64 v85, v86, v84, s[98:99]
	v_cndmask_b32_e64 v101, v102, v100, s[98:99]
	v_cndmask_b32_e64 v133, v134, v132, s[98:99]
	v_mov_b32_dpp v119, v117 quad_perm:[2,3,0,1] row_mask:0xf bank_mask:0xf
	v_mov_b32_dpp v87, v85 quad_perm:[2,3,0,1] row_mask:0xf bank_mask:0xf
	v_mov_b32_dpp v103, v101 quad_perm:[2,3,0,1] row_mask:0xf bank_mask:0xf
	v_mov_b32_dpp v135, v133 quad_perm:[2,3,0,1] row_mask:0xf bank_mask:0xf
	v_cndmask_b32_e64 v117, v119, v118, s[98:99]
	v_cndmask_b32_e64 v85, v87, v86, s[98:99]
	v_cndmask_b32_e64 v101, v103, v102, s[98:99]
	v_cndmask_b32_e64 v133, v135, v134, s[98:99]
	v_cndmask_b32_e64 v116, v116, v119, s[98:99]
	v_cndmask_b32_e64 v84, v84, v87, s[98:99]
	v_cndmask_b32_e64 v100, v100, v103, s[98:99]
; __device__ __forceinline__ bf16_t f2bf(float f) { unsigned u = __float_as_uint(f); u += 0x7FFFu + ((u >> 16) & 1u); return (bf16_t)(u >> 16); }
; __device__ __forceinline__ void sb_unit(LAS unsigned char* lds, const bf16_t* qkv, bf16_t* attout, int b, int h, int qb, int wid, int) {
;     ...
;     asm volatile("" : "+v"(hi), "+v"(r32));
;     bf16_t* op = attout + (size_t)(b * SEQ + q0 + 4 * hi) * DM + h * 128 + r32;
; #pragma unroll
;     for (int r = 0; r < 16; ++r) {
; #pragma unroll
;         for (int d0 = 0; d0 < 4; ++d0) op[d0 * 32] = f2bf(o[d0][r]);
;         op += ((r & 3) == 3 ? 5 : 1) * DM; asm volatile("" : "+v"(op) :: "memory"); }
	v_cndmask_b32_e64 v132, v132, v135, s[98:99]
	global_store_dwordx2 v[2:3], v[116:117], off
	global_store_dwordx2 v[2:3], v[84:85], off offset:64
	global_store_dwordx2 v[2:3], v[100:101], off offset:128
	global_store_dwordx2 v[2:3], v[132:133], off offset:192
	v_lshl_add_u64 v[2:3], v[2:3], 0, s[100:101]
	v_cvt_pk_bf16_f32 v120, v120, v121
	v_cvt_pk_bf16_f32 v88, v88, v89
	v_cvt_pk_bf16_f32 v104, v104, v105
	v_cvt_pk_bf16_f32 v136, v136, v137
	v_cvt_pk_bf16_f32 v122, v122, v123
	v_cvt_pk_bf16_f32 v90, v90, v91
	v_cvt_pk_bf16_f32 v106, v106, v107
	v_cvt_pk_bf16_f32 v138, v138, v139
	v_mov_b32_dpp v121, v120 quad_perm:[1,0,3,2] row_mask:0xf bank_mask:0xf
	v_mov_b32_dpp v89, v88 quad_perm:[1,0,3,2] row_mask:0xf bank_mask:0xf
	v_mov_b32_dpp v105, v104 quad_perm:[1,0,3,2] row_mask:0xf bank_mask:0xf
	v_mov_b32_dpp v137, v136 quad_perm:[1,0,3,2] row_mask:0xf bank_mask:0xf
	v_mov_b32_dpp v123, v122 quad_perm:[1,0,3,2] row_mask:0xf bank_mask:0xf
	v_mov_b32_dpp v91, v90 quad_perm:[1,0,3,2] row_mask:0xf bank_mask:0xf
	v_mov_b32_dpp v107, v106 quad_perm:[1,0,3,2] row_mask:0xf bank_mask:0xf
	v_mov_b32_dpp v139, v138 quad_perm:[1,0,3,2] row_mask:0xf bank_mask:0xf
	v_perm_b32 v120, v120, v121, v0
	v_perm_b32 v88, v88, v89, v0
	v_perm_b32 v104, v104, v105, v0
	v_perm_b32 v136, v136, v137, v0
	v_perm_b32 v122, v122, v123, v0
	v_perm_b32 v90, v90, v91, v0
	v_perm_b32 v106, v106, v107, v0
	v_perm_b32 v138, v138, v139, v0
	v_cndmask_b32_e64 v121, v122, v120, s[98:99]
	v_cndmask_b32_e64 v89, v90, v88, s[98:99]
	v_cndmask_b32_e64 v105, v106, v104, s[98:99]
	v_cndmask_b32_e64 v137, v138, v136, s[98:99]
	v_mov_b32_dpp v123, v121 quad_perm:[2,3,0,1] row_mask:0xf bank_mask:0xf
	v_mov_b32_dpp v91, v89 quad_perm:[2,3,0,1] row_mask:0xf bank_mask:0xf
	v_mov_b32_dpp v107, v105 quad_perm:[2,3,0,1] row_mask:0xf bank_mask:0xf
	v_mov_b32_dpp v139, v137 quad_perm:[2,3,0,1] row_mask:0xf bank_mask:0xf
	v_cndmask_b32_e64 v121, v123, v122, s[98:99]
	v_cndmask_b32_e64 v89, v91, v90, s[98:99]
	v_cndmask_b32_e64 v105, v107, v106, s[98:99]
	v_cndmask_b32_e64 v137, v139, v138, s[98:99]
	v_cndmask_b32_e64 v120, v120, v123, s[98:99]
	v_cndmask_b32_e64 v88, v88, v91, s[98:99]
	v_cndmask_b32_e64 v104, v104, v107, s[98:99]
	v_cndmask_b32_e64 v136, v136, v139, s[98:99]
	global_store_dwordx2 v[2:3], v[120:121], off
	global_store_dwordx2 v[2:3], v[88:89], off offset:64
	global_store_dwordx2 v[2:3], v[104:105], off offset:128
	global_store_dwordx2 v[2:3], v[136:137], off offset:192
	v_lshl_add_u64 v[2:3], v[2:3], 0, s[100:101]
	v_cvt_pk_bf16_f32 v124, v124, v125
	v_cvt_pk_bf16_f32 v92, v92, v93
	v_cvt_pk_bf16_f32 v108, v108, v109
	v_cvt_pk_bf16_f32 v140, v140, v141
	v_cvt_pk_bf16_f32 v126, v126, v127
	v_cvt_pk_bf16_f32 v94, v94, v95
	v_cvt_pk_bf16_f32 v110, v110, v111
	v_cvt_pk_bf16_f32 v142, v142, v143
	v_mov_b32_dpp v125, v124 quad_perm:[1,0,3,2] row_mask:0xf bank_mask:0xf
	v_mov_b32_dpp v93, v92 quad_perm:[1,0,3,2] row_mask:0xf bank_mask:0xf
	v_mov_b32_dpp v109, v108 quad_perm:[1,0,3,2] row_mask:0xf bank_mask:0xf
	v_mov_b32_dpp v141, v140 quad_perm:[1,0,3,2] row_mask:0xf bank_mask:0xf
	v_mov_b32_dpp v127, v126 quad_perm:[1,0,3,2] row_mask:0xf bank_mask:0xf
	v_mov_b32_dpp v95, v94 quad_perm:[1,0,3,2] row_mask:0xf bank_mask:0xf
	v_mov_b32_dpp v111, v110 quad_perm:[1,0,3,2] row_mask:0xf bank_mask:0xf
	v_mov_b32_dpp v143, v142 quad_perm:[1,0,3,2] row_mask:0xf bank_mask:0xf
	v_perm_b32 v124, v124, v125, v0
	v_perm_b32 v92, v92, v93, v0
	v_perm_b32 v108, v108, v109, v0
	v_perm_b32 v140, v140, v141, v0
	v_perm_b32 v126, v126, v127, v0
	v_perm_b32 v94, v94, v95, v0
	v_perm_b32 v110, v110, v111, v0
	v_perm_b32 v142, v142, v143, v0
	v_cndmask_b32_e64 v125, v126, v124, s[98:99]
	v_cndmask_b32_e64 v93, v94, v92, s[98:99]
	v_cndmask_b32_e64 v109, v110, v108, s[98:99]
	v_cndmask_b32_e64 v141, v142, v140, s[98:99]
	v_mov_b32_dpp v127, v125 quad_perm:[2,3,0,1] row_mask:0xf bank_mask:0xf
	v_mov_b32_dpp v95, v93 quad_perm:[2,3,0,1] row_mask:0xf bank_mask:0xf
	v_mov_b32_dpp v111, v109 quad_perm:[2,3,0,1] row_mask:0xf bank_mask:0xf
	v_mov_b32_dpp v143, v141 quad_perm:[2,3,0,1] row_mask:0xf bank_mask:0xf
	v_cndmask_b32_e64 v125, v127, v126, s[98:99]
	v_cndmask_b32_e64 v93, v95, v94, s[98:99]
	v_cndmask_b32_e64 v109, v111, v110, s[98:99]
	v_cndmask_b32_e64 v141, v143, v142, s[98:99]
	v_cndmask_b32_e64 v124, v124, v127, s[98:99]
	v_cndmask_b32_e64 v92, v92, v95, s[98:99]
	v_cndmask_b32_e64 v108, v108, v111, s[98:99]
	v_cndmask_b32_e64 v140, v140, v143, s[98:99]
	global_store_dwordx2 v[2:3], v[124:125], off
	global_store_dwordx2 v[2:3], v[92:93], off offset:64
	global_store_dwordx2 v[2:3], v[108:109], off offset:128
	global_store_dwordx2 v[2:3], v[140:141], off offset:192
	v_lshl_add_u64 v[2:3], v[2:3], 0, s[100:101]
	s_add_i32 s70, s70, s69
	s_cmpk_lt_i32 s70, 0x200
	s_cbranch_scc0 .LBB0_347
